# Hyena context-token direct convolution loop (layer 0): 12 LDS reads per 8-tap step issued up front with counted waits
# baseline (speedup 1.0000x reference)
; DI void hyena_unit(KP p, int l, int c, char* smem) {
;     ...
;       {
;         f32x4 y = mkf4(0.f, 0.f, 0.f, 0.f);
; #pragma unroll 8
;         for (int s2 = 0; s2 < 256; ++s2) { const float kv = kk[255 + t - s2]; const f32x4 u4 = ((const f32x4*)uu)[s2]; y += kv * u4; }
;         const f32x4 ut = ((const f32x4*)uu)[t];
;         const float yy[4] = {y.x, y.y, y.z, y.w}, us[4] = {ut.x, ut.y, ut.z, ut.w};
; #pragma unroll
;         for (int b = 0; b < 4; ++b) {
;           const float xg = sconv3(Zhc + (size_t)(b * 1536 + gcol) * 256, t, 256, gw0, gw1, gw2, gb);
;           const float ov = xg * yy[b];
.LBB0_1052:
	v_add_u32_e32 v51, s17, v44
	v_mov_b32_e32 v64, s16
	ds_read2_b32 v[132:133], v51 offset0:6 offset1:7
	ds_read_b128 v[140:143], v64
	ds_read_b128 v[144:147], v64 offset:16
	ds_read2_b32 v[134:135], v51 offset0:4 offset1:5
	ds_read_b128 v[148:151], v64 offset:32
	ds_read_b128 v[152:155], v64 offset:48
	ds_read2_b32 v[136:137], v51 offset0:2 offset1:3
	ds_read_b128 v[156:159], v64 offset:64
	ds_read_b128 v[160:163], v64 offset:80
	ds_read2_b32 v[138:139], v51 offset0:0 offset1:1
	ds_read_b128 v[164:167], v64 offset:96
	ds_read_b128 v[168:171], v64 offset:112
	s_addk_i32 s16, 0x80
	s_sub_i32 s17, s17, 32
	s_cmpk_eq_i32 s17, 0xffe0
	s_waitcnt lgkmcnt(10)
	v_pk_fma_f32 v[8:9], v[140:141], v[132:133], v[8:9] op_sel:[0,1,0]
	v_pk_fma_f32 v[6:7], v[142:143], v[132:133], v[6:7] op_sel:[0,1,0]
	s_waitcnt lgkmcnt(9)
	v_pk_fma_f32 v[8:9], v[144:145], v[132:133], v[8:9] op_sel_hi:[1,0,1]
	v_pk_fma_f32 v[6:7], v[146:147], v[132:133], v[6:7] op_sel_hi:[1,0,1]
	s_waitcnt lgkmcnt(7)
	v_pk_fma_f32 v[8:9], v[148:149], v[134:135], v[8:9] op_sel:[0,1,0]
	v_pk_fma_f32 v[6:7], v[150:151], v[134:135], v[6:7] op_sel:[0,1,0]
	s_waitcnt lgkmcnt(6)
	v_pk_fma_f32 v[8:9], v[152:153], v[134:135], v[8:9] op_sel_hi:[1,0,1]
	v_pk_fma_f32 v[6:7], v[154:155], v[134:135], v[6:7] op_sel_hi:[1,0,1]
	s_waitcnt lgkmcnt(4)
	v_pk_fma_f32 v[8:9], v[156:157], v[136:137], v[8:9] op_sel:[0,1,0]
	v_pk_fma_f32 v[6:7], v[158:159], v[136:137], v[6:7] op_sel:[0,1,0]
	s_waitcnt lgkmcnt(3)
	v_pk_fma_f32 v[8:9], v[160:161], v[136:137], v[8:9] op_sel_hi:[1,0,1]
	v_pk_fma_f32 v[6:7], v[162:163], v[136:137], v[6:7] op_sel_hi:[1,0,1]
	s_waitcnt lgkmcnt(1)
	v_pk_fma_f32 v[8:9], v[164:165], v[138:139], v[8:9] op_sel:[0,1,0]
	v_pk_fma_f32 v[6:7], v[166:167], v[138:139], v[6:7] op_sel:[0,1,0]
	s_waitcnt lgkmcnt(0)
	v_pk_fma_f32 v[8:9], v[168:169], v[138:139], v[8:9] op_sel_hi:[1,0,1]
	v_pk_fma_f32 v[6:7], v[170:171], v[138:139], v[6:7] op_sel_hi:[1,0,1]
	s_cbranch_scc0 .LBB0_1052
	s_add_i32 s16, s7, s86
	s_ashr_i32 s17, s16, 31
	s_lshl_b64 s[24:25], s[16:17], 9
	s_add_u32 s16, s29, s24
	s_addc_u32 s17, s34, s25
	s_waitcnt vmcnt(0)
	v_lshlrev_b32_e32 v13, 16, v104
	v_lshlrev_b32_e32 v12, 16, v106
	v_mov_b32_e32 v40, v105
	v_cndmask_b32_e64 v13, 0, v13, s[12:13]
	v_cndmask_b32_e64 v12, 0, v12, s[14:15]
	s_waitcnt vmcnt(0)
	v_lshlrev_b32_e32 v10, 16, v40
	v_mul_f32_e32 v10, v49, v10
	v_fmac_f32_e32 v10, v47, v13
	v_fmac_f32_e32 v10, v48, v12
	v_add_f32_e32 v10, v50, v10
	v_mul_f32_e32 v8, v8, v10
	s_and_b64 vcc, exec, s[22:23]
	s_cbranch_vccz .LBB0_1061
	v_cvt_pk_bf16_f32 v8, v8, s0
	global_store_short v[32:33], v8, off
	s_branch .LBB0_1062
